# on top of v20: merge_conv output (y) stores also write-through (sc1); out-proj stores left write-back after a bisect showed no gain there
# baseline (speedup 1.0000x reference)
; #define GAS __attribute__((address_space(1)))
; __device__ __forceinline__ void merge_conv(const GAS bf16* proj, const GAS bf16* part, const GAS float* lse, GAS bf16* y, int TOKG, const GAS float* convw, int lane, int gw, int ngw) {
;     ...
;     for (int it0 = 2 * gw; it0 < TOKG; it0 += 2 * ngw) {
;         const int t = it0 & (SEQ - 1); const GAS bf16* prow = proj + (size_t)it0 * PW;
; #pragma unroll
;         for (int i = 0; i < 2; ++i) { const int c0 = lane * 8 + 512 * i;
;             float u[4][8];
; #pragma unroll
;             for (int k = 0; k < 4; ++k) { const int tt = t - 2 + k;
;                 if (tt >= 0) { const GAS bf16* pr = prow + ((ptrdiff_t)k - 2) * PW; float gc[8], xa[8];
;                     unpack8(*(const GAS v4u*)(pr + 1024 + c0), gc); unpack8(*(const GAS v4u*)(pr + 2048 + c0), xa);
; #pragma unroll
;                     for (int e = 0; e < 8; ++e) u[k][e] = gc[e] * xa[e]; }
;                 else {
; #pragma unroll
;                     for (int e = 0; e < 8; ++e) u[k][e] = 0.f; } }
; #pragma unroll
;             for (int q = 0; q < 2; ++q) { const GAS bf16* pq = prow + (size_t)q * PW;
;                 float gb[8], z[8], r[8]; unpack8(*(const GAS v4u*)(pq + c0), gb); unpack8(*(const GAS v4u*)(pq + 6144 + c0), z);
; #pragma unroll
;                 for (int e = 0; e < 8; ++e) r[e] = gb[e] * (cw[i][0][e] * u[q][e] + cw[i][1][e] * u[q + 1][e] + cw[i][2][e] * u[q + 2][e]) * z[e];
;                 v4u o; o.x = pk2(r[0], r[1]); o.y = pk2(r[2], r[3]); o.z = pk2(r[4], r[5]); o.w = pk2(r[6], r[7]);
;                 *(GAS v4u*)(y + (size_t)(it0 + q) * MW + c0) = o; } }
; #pragma unroll
;         for (int q = 0; q < 2; ++q) { const int it = it0 + q; const GAS bf16* pq = prow + (size_t)q * PW;
; #pragma unroll
;             for (int i = 0; i < 2; ++i) { const int c0 = lane * 8 + 512 * i, h = c0 >> 6;
;                 const float l0 = lse[((size_t)0 * TOKG + it) * 16 + h], l1 = lse[((size_t)1 * TOKG + it) * 16 + h], l2 = lse[((size_t)2 * TOKG + it) * 16 + h];
;                 const float mx = fmaxf(l0, fmaxf(l1, l2)); float w0 = __expf(l0 - mx), w1 = __expf(l1 - mx), w2 = __expf(l2 - mx); const float inv = __builtin_amdgcn_rcpf(w0 + w1 + w2); w0 *= inv; w1 *= inv; w2 *= inv;
.LBB0_404:
	global_load_dwordx4 v[114:117], v[96:97], off offset:3072
	global_load_dwordx4 v[118:121], v[98:99], off offset:1024
	global_load_dwordx4 v[48:51], v[92:93], off offset:3072
	global_load_dwordx4 v[52:55], v[100:101], off offset:1024
	global_load_dwordx4 v[122:125], v[96:97], off offset:1024
	global_load_dwordx4 v[126:129], v[90:91], off offset:1024
	v_pk_mul_f32 v[100:101], v[24:25], v[106:107]
	s_add_i32 s6, s6, s52
	v_pk_fma_f32 v[100:101], v[8:9], v[110:111], v[100:101]
	v_lshl_add_u64 v[70:71], v[70:71], 0, s[70:71]
	v_lshl_add_u64 v[88:89], v[88:89], 0, s[82:83]
	s_cmp_ge_i32 s6, s96
	s_waitcnt vmcnt(5)
	v_lshlrev_b32_e32 v94, 16, v114
	v_and_b32_e32 v95, 0xffff0000, v114
	s_waitcnt vmcnt(4)
	v_lshlrev_b32_e32 v96, 16, v118
	v_and_b32_e32 v97, 0xffff0000, v118
	v_pk_mul_f32 v[94:95], v[94:95], v[96:97]
	s_waitcnt vmcnt(1)
	v_lshlrev_b32_e32 v96, 16, v122
	v_and_b32_e32 v97, 0xffff0000, v122
	v_pk_fma_f32 v[100:101], v[0:1], v[94:95], v[100:101]
	s_waitcnt vmcnt(0)
	v_lshlrev_b32_e32 v98, 16, v126
	v_and_b32_e32 v99, 0xffff0000, v126
	v_pk_mul_f32 v[96:97], v[100:101], v[96:97]
	v_lshlrev_b32_e32 v100, 16, v119
	v_pk_mul_f32 v[98:99], v[96:97], v[98:99]
	v_lshlrev_b32_e32 v96, 16, v115
	v_and_b32_e32 v97, 0xffff0000, v115
	v_and_b32_e32 v101, 0xffff0000, v119
	v_pk_mul_f32 v[114:115], v[26:27], v[104:105]
	v_pk_mul_f32 v[96:97], v[96:97], v[100:101]
	v_pk_fma_f32 v[108:109], v[10:11], v[108:109], v[114:115]
	v_lshlrev_b32_e32 v100, 16, v123
	v_and_b32_e32 v101, 0xffff0000, v123
	v_pk_fma_f32 v[108:109], v[2:3], v[96:97], v[108:109]
	v_lshlrev_b32_e32 v110, 16, v127
	v_and_b32_e32 v111, 0xffff0000, v127
	v_pk_mul_f32 v[100:101], v[108:109], v[100:101]
	v_pk_mul_f32 v[118:119], v[4:5], v[102:103]
	v_pk_mul_f32 v[108:109], v[100:101], v[110:111]
	v_lshlrev_b32_e32 v100, 16, v116
	v_and_b32_e32 v101, 0xffff0000, v116
	v_lshlrev_b32_e32 v110, 16, v120
	v_and_b32_e32 v111, 0xffff0000, v120
	v_pk_mul_f32 v[100:101], v[100:101], v[110:111]
	v_pk_fma_f32 v[66:67], v[12:13], v[66:67], v[118:119]
	v_lshlrev_b32_e32 v110, 16, v124
	v_and_b32_e32 v111, 0xffff0000, v124
	v_pk_fma_f32 v[66:67], v[16:17], v[100:101], v[66:67]
	v_lshlrev_b32_e32 v114, 16, v128
	v_and_b32_e32 v115, 0xffff0000, v128
	v_pk_mul_f32 v[66:67], v[66:67], v[110:111]
	v_pk_mul_f32 v[118:119], v[6:7], v[58:59]
	v_pk_mul_f32 v[110:111], v[66:67], v[114:115]
	v_lshlrev_b32_e32 v66, 16, v117
	v_and_b32_e32 v67, 0xffff0000, v117
	v_lshlrev_b32_e32 v114, 16, v121
	v_and_b32_e32 v115, 0xffff0000, v121
	v_pk_mul_f32 v[66:67], v[66:67], v[114:115]
	v_pk_fma_f32 v[64:65], v[14:15], v[64:65], v[118:119]
	v_lshlrev_b32_e32 v116, 16, v125
	v_and_b32_e32 v117, 0xffff0000, v125
	v_pk_fma_f32 v[64:65], v[18:19], v[66:67], v[64:65]
	v_lshlrev_b32_e32 v114, 16, v129
	v_and_b32_e32 v115, 0xffff0000, v129
	v_pk_mul_f32 v[64:65], v[64:65], v[116:117]
	v_cvt_pk_bf16_f32 v116, v110, v111
	v_pk_mul_f32 v[64:65], v[64:65], v[114:115]
	v_cvt_pk_bf16_f32 v114, v98, v99
	v_cvt_pk_bf16_f32 v115, v108, v109
	v_cvt_pk_bf16_f32 v117, v64, v65
	global_store_dwordx4 v[60:61], v[114:117], off offset:1024 sc1
	global_load_dwordx4 v[108:111], v[92:93], off offset:1024
	s_nop 0
	global_load_dwordx4 v[114:117], v[56:57], off offset:1024
	v_lshlrev_b32_e32 v64, 16, v52
	v_and_b32_e32 v65, 0xffff0000, v52
	v_lshlrev_b32_e32 v92, 16, v48
	v_and_b32_e32 v93, 0xffff0000, v48
	v_pk_mul_f32 v[94:95], v[24:25], v[94:95]
	v_pk_mul_f32 v[64:65], v[92:93], v[64:65]
	v_pk_fma_f32 v[94:95], v[8:9], v[106:107], v[94:95]
	v_lshlrev_b32_e32 v52, 16, v53
	v_pk_fma_f32 v[64:65], v[0:1], v[64:65], v[94:95]
	v_and_b32_e32 v53, 0xffff0000, v53
	v_lshlrev_b32_e32 v48, 16, v49
	v_and_b32_e32 v49, 0xffff0000, v49
	v_pk_mul_f32 v[94:95], v[26:27], v[96:97]
	v_pk_mul_f32 v[48:49], v[48:49], v[52:53]
	v_pk_fma_f32 v[94:95], v[10:11], v[104:105], v[94:95]
	v_pk_mul_f32 v[96:97], v[4:5], v[100:101]
	v_pk_fma_f32 v[48:49], v[2:3], v[48:49], v[94:95]
	v_pk_fma_f32 v[96:97], v[12:13], v[102:103], v[96:97]
	v_pk_mul_f32 v[66:67], v[6:7], v[66:67]
	s_waitcnt vmcnt(1)
	v_lshlrev_b32_e32 v92, 16, v108
	v_and_b32_e32 v93, 0xffff0000, v108
	v_lshlrev_b32_e32 v52, 16, v109
	v_and_b32_e32 v53, 0xffff0000, v109
	v_pk_mul_f32 v[64:65], v[64:65], v[92:93]
	s_waitcnt vmcnt(0)
	v_lshlrev_b32_e32 v92, 16, v115
	v_and_b32_e32 v93, 0xffff0000, v115
	v_pk_mul_f32 v[48:49], v[48:49], v[52:53]
	v_lshlrev_b32_e32 v94, 16, v116
	v_pk_mul_f32 v[52:53], v[48:49], v[92:93]
	v_lshlrev_b32_e32 v48, 16, v54
	v_and_b32_e32 v49, 0xffff0000, v54
	v_lshlrev_b32_e32 v92, 16, v50
	v_and_b32_e32 v93, 0xffff0000, v50
	v_pk_mul_f32 v[48:49], v[92:93], v[48:49]
	v_lshlrev_b32_e32 v92, 16, v110
	v_and_b32_e32 v93, 0xffff0000, v110
	v_pk_fma_f32 v[48:49], v[16:17], v[48:49], v[96:97]
	v_and_b32_e32 v95, 0xffff0000, v116
	v_pk_mul_f32 v[48:49], v[48:49], v[92:93]
	v_lshlrev_b32_e32 v50, 16, v51
	v_pk_mul_f32 v[92:93], v[48:49], v[94:95]
	v_lshlrev_b32_e32 v48, 16, v55
	v_and_b32_e32 v49, 0xffff0000, v55
	v_and_b32_e32 v51, 0xffff0000, v51
	v_pk_mul_f32 v[48:49], v[50:51], v[48:49]
	v_pk_fma_f32 v[58:59], v[14:15], v[58:59], v[66:67]
	v_lshlrev_b32_e32 v50, 16, v111
	v_and_b32_e32 v51, 0xffff0000, v111
	v_pk_fma_f32 v[48:49], v[18:19], v[48:49], v[58:59]
	v_lshlrev_b32_e32 v98, 16, v114
	v_and_b32_e32 v99, 0xffff0000, v114
	v_lshlrev_b32_e32 v54, 16, v117
	v_and_b32_e32 v55, 0xffff0000, v117
	v_pk_mul_f32 v[48:49], v[48:49], v[50:51]
	v_pk_mul_f32 v[64:65], v[64:65], v[98:99]
	v_pk_mul_f32 v[54:55], v[48:49], v[54:55]
	v_cvt_pk_bf16_f32 v49, v52, v53
	v_add_co_u32_e32 v52, vcc, s68, v62
	v_cvt_pk_bf16_f32 v48, v64, v65
	v_cvt_pk_bf16_f32 v50, v92, v93
	v_cvt_pk_bf16_f32 v51, v54, v55
	v_addc_co_u32_e32 v53, vcc, 0, v63, vcc
	global_store_dwordx4 v[52:53], v[48:51], off offset:1024 sc1
	v_lshl_add_u64 v[58:59], s[0:1], 0, v[68:69]
	v_lshl_add_u64 v[54:55], s[0:1], 0, v[78:79]
	v_lshl_add_u64 v[48:49], s[0:1], 0, v[86:87]
	v_add_co_u32_e32 v62, vcc, s86, v48
	v_lshl_add_u64 v[64:65], s[0:1], 0, v[76:77]
	s_nop 0
	v_addc_co_u32_e32 v63, vcc, 0, v49, vcc
	v_lshl_add_u64 v[48:49], s[0:1], 0, v[82:83]
	v_add_co_u32_e32 v66, vcc, s86, v48
	global_load_dword v50, v[62:63], off
	s_nop 0
	v_addc_co_u32_e32 v67, vcc, 0, v49, vcc
	v_lshl_add_u64 v[48:49], s[0:1], 0, v[74:75]
	v_add_co_u32_e32 v92, vcc, s86, v48
	global_load_dword v51, v[66:67], off
	s_nop 0
	v_addc_co_u32_e32 v93, vcc, 0, v49, vcc
	global_load_dword v48, v[92:93], off
	v_lshl_add_u64 v[68:69], v[68:69], 0, s[66:67]
	v_lshl_add_u64 v[74:75], v[74:75], 0, s[62:63]
	v_lshl_add_u64 v[76:77], v[76:77], 0, s[66:67]
	v_lshl_add_u64 v[78:79], v[78:79], 0, s[66:67]
	v_lshl_add_u64 v[82:83], v[82:83], 0, s[62:63]
	v_lshl_add_u64 v[86:87], v[86:87], 0, s[62:63]
	global_load_dwordx4 v[100:103], v[54:55], off offset:-2048
	s_waitcnt vmcnt(1)
; #define GAS __attribute__((address_space(1)))
; __device__ __forceinline__ unsigned pk2(float lo, float hi) { const f32x2_t v = {lo, hi}; const bf16x2_t b = __builtin_convertvector(v, bf16x2_t); return __builtin_bit_cast(unsigned, b); }
; __device__ __forceinline__ void merge_conv(const GAS bf16* proj, const GAS bf16* part, const GAS float* lse, GAS bf16* y, int TOKG, const GAS float* convw, int lane, int gw, int ngw) {
;     ...
;         for (int q = 0; q < 2; ++q) { const int it = it0 + q; const GAS bf16* pq = prow + (size_t)q * PW;
; #pragma unroll
;             for (int i = 0; i < 2; ++i) { const int c0 = lane * 8 + 512 * i, h = c0 >> 6;
;                 const float l0 = lse[((size_t)0 * TOKG + it) * 16 + h], l1 = lse[((size_t)1 * TOKG + it) * 16 + h], l2 = lse[((size_t)2 * TOKG + it) * 16 + h];
;                 const float mx = fmaxf(l0, fmaxf(l1, l2)); float w0 = __expf(l0 - mx), w1 = __expf(l1 - mx), w2 = __expf(l2 - mx); const float inv = __builtin_amdgcn_rcpf(w0 + w1 + w2); w0 *= inv; w1 *= inv; w2 *= inv;
;                 float a0[8], a1[8], a2[8], z[8];
;                 unpack8(*(const GAS v4u*)(part + ((size_t)0 * TOKG + it) * 1024 + c0), a0); unpack8(*(const GAS v4u*)(part + ((size_t)1 * TOKG + it) * 1024 + c0), a1); unpack8(*(const GAS v4u*)(part + ((size_t)2 * TOKG + it) * 1024 + c0), a2);
;                 unpack8(*(const GAS v4u*)(pq + 6144 + 1024 + c0), z);
;                 float r[8];
; #pragma unroll
;                 for (int e = 0; e < 8; ++e) r[e] = (w0 * a0[e] + w1 * a1[e] + w2 * a2[e]) * z[e];
;                 v4u o; o.x = pk2(r[0], r[1]); o.y = pk2(r[2], r[3]); o.z = pk2(r[4], r[5]); o.w = pk2(r[6], r[7]);
;                 *(GAS v4u*)(y + (size_t)it * MW + 1024 + c0) = o; } }
	v_max3_f32 v49, v50, v51, v48
	v_sub_f32_e32 v50, v50, v49
	v_mul_f32_e32 v50, 0x3fb8aa3b, v50
	v_exp_f32_e32 v97, v50
	v_sub_f32_e32 v50, v51, v49
	v_mul_f32_e32 v50, 0x3fb8aa3b, v50
	v_sub_f32_e32 v48, v48, v49
	v_exp_f32_e32 v96, v50
	v_mul_f32_e32 v48, 0x3fb8aa3b, v48
	v_exp_f32_e32 v48, v48
	s_waitcnt vmcnt(0)
	v_and_b32_e32 v123, 0xffff0000, v100
	v_add_f32_e32 v49, v97, v96
	v_lshlrev_b32_e32 v120, 16, v100
	v_add_f32_e32 v49, v48, v49
	v_rcp_f32_e32 v98, v49
	v_and_b32_e32 v115, 0xffff0000, v103
	v_mul_f32_e32 v94, v48, v98
	global_load_dwordx4 v[48:51], v[58:59], off offset:-2048
	global_load_dwordx4 v[104:107], v[64:65], off offset:-2048
	global_load_dwordx4 v[108:111], v[90:91], off offset:2048
	v_pk_mul_f32 v[96:97], v[96:97], v[98:99] op_sel_hi:[1,0]
	v_lshlrev_b32_e32 v98, 16, v103
	s_waitcnt vmcnt(2)
	v_lshlrev_b32_e32 v122, 16, v48
	v_and_b32_e32 v121, 0xffff0000, v48
	v_pk_mul_f32 v[122:123], v[96:97], v[122:123] op_sel:[1,0] op_sel_hi:[0,1]
	v_pk_fma_f32 v[120:121], v[96:97], v[120:121], v[122:123]
	v_and_b32_e32 v123, 0xffff0000, v49
	v_lshlrev_b32_e32 v48, 16, v49
	v_and_b32_e32 v49, 0xffff0000, v101
	v_lshlrev_b32_e32 v122, 16, v101
	v_pk_mul_f32 v[48:49], v[96:97], v[48:49] op_sel:[1,0] op_sel_hi:[0,1]
	s_waitcnt vmcnt(1)
	v_lshlrev_b32_e32 v100, 16, v105
	v_and_b32_e32 v101, 0xffff0000, v105
	v_pk_fma_f32 v[48:49], v[96:97], v[122:123], v[48:49]
	v_lshlrev_b32_e32 v124, 16, v104
	v_and_b32_e32 v125, 0xffff0000, v104
	s_waitcnt vmcnt(0)
	v_lshlrev_b32_e32 v104, 16, v109
	v_and_b32_e32 v105, 0xffff0000, v109
	v_pk_fma_f32 v[48:49], v[94:95], v[100:101], v[48:49] op_sel_hi:[0,1,1]
	v_and_b32_e32 v99, 0xffff0000, v51
	v_lshlrev_b32_e32 v114, 16, v51
	v_pk_mul_f32 v[100:101], v[48:49], v[104:105]
	v_and_b32_e32 v49, 0xffff0000, v50
	v_lshlrev_b32_e32 v50, 16, v50
	v_and_b32_e32 v51, 0xffff0000, v102
	v_lshlrev_b32_e32 v48, 16, v102
	v_pk_mul_f32 v[50:51], v[96:97], v[50:51] op_sel:[1,0] op_sel_hi:[0,1]
	v_lshlrev_b32_e32 v102, 16, v106
	v_and_b32_e32 v103, 0xffff0000, v106
	v_pk_fma_f32 v[48:49], v[96:97], v[48:49], v[50:51]
	v_lshlrev_b32_e32 v104, 16, v110
	v_and_b32_e32 v105, 0xffff0000, v110
	v_pk_fma_f32 v[48:49], v[94:95], v[102:103], v[48:49] op_sel_hi:[0,1,1]
	v_pk_mul_f32 v[50:51], v[48:49], v[104:105]
	v_pk_mul_f32 v[48:49], v[96:97], v[114:115] op_sel:[1,0] op_sel_hi:[0,1]
	v_lshlrev_b32_e32 v116, 16, v107
	v_and_b32_e32 v117, 0xffff0000, v107
	v_pk_fma_f32 v[48:49], v[96:97], v[98:99], v[48:49]
	v_lshlrev_b32_e32 v118, 16, v111
	v_and_b32_e32 v119, 0xffff0000, v111
	v_lshlrev_b32_e32 v126, 16, v108
	v_and_b32_e32 v127, 0xffff0000, v108
	v_pk_fma_f32 v[120:121], v[94:95], v[124:125], v[120:121] op_sel_hi:[0,1,1]
	v_pk_fma_f32 v[48:49], v[94:95], v[116:117], v[48:49] op_sel_hi:[0,1,1]
	v_pk_mul_f32 v[120:121], v[120:121], v[126:127]
	v_pk_mul_f32 v[94:95], v[48:49], v[118:119]
	v_cvt_pk_bf16_f32 v48, v120, v121
	v_cvt_pk_bf16_f32 v49, v100, v101
	v_cvt_pk_bf16_f32 v50, v50, v51
	v_cvt_pk_bf16_f32 v51, v94, v95
	global_store_dwordx4 v[60:61], v[48:51], off offset:2048 sc1
	v_lshl_add_u64 v[94:95], s[0:1], 0, v[72:73]
	v_lshl_add_u64 v[72:73], v[72:73], 0, s[62:63]
	v_lshl_add_u64 v[48:49], s[0:1], 0, v[84:85]
	v_add_co_u32_e32 v48, vcc, s86, v48
	v_lshl_add_u64 v[50:51], s[0:1], 0, v[80:81]
	s_nop 0
	v_addc_co_u32_e32 v49, vcc, 0, v49, vcc
	v_add_co_u32_e32 v50, vcc, s86, v50
	global_load_dword v96, v[48:49], off
	s_nop 0
	v_addc_co_u32_e32 v51, vcc, 0, v51, vcc
	v_add_co_u32_e32 v94, vcc, s86, v94
	global_load_dword v97, v[50:51], off
	s_nop 0
	v_addc_co_u32_e32 v95, vcc, 0, v95, vcc
	global_load_dword v98, v[94:95], off
	v_lshl_add_u64 v[80:81], v[80:81], 0, s[62:63]
	v_lshl_add_u64 v[84:85], v[84:85], 0, s[62:63]
	s_waitcnt vmcnt(0)
	v_max3_f32 v99, v96, v97, v98
	v_sub_f32_e32 v96, v96, v99
	v_mul_f32_e32 v96, 0x3fb8aa3b, v96
	v_exp_f32_e32 v111, v96
	v_sub_f32_e32 v96, v97, v99
	v_mul_f32_e32 v96, 0x3fb8aa3b, v96
	v_exp_f32_e32 v110, v96
	v_sub_f32_e32 v96, v98, v99
	global_load_dwordx4 v[98:101], v[58:59], off offset:-1024
	global_load_dwordx4 v[102:105], v[54:55], off offset:-1024
	global_load_dwordx4 v[106:109], v[64:65], off offset:-1024
	global_load_dwordx4 v[114:117], v[90:91], off offset:3072
	v_mul_f32_e32 v96, 0x3fb8aa3b, v96
	v_exp_f32_e32 v96, v96
	v_add_f32_e32 v97, v111, v110
	v_add_f32_e32 v97, v96, v97
	v_rcp_f32_e32 v112, v97
	s_waitcnt vmcnt(3)
	v_lshlrev_b32_e32 v126, 16, v98
	v_pk_mul_f32 v[90:91], v[110:111], v[112:113] op_sel_hi:[1,0]
	s_waitcnt vmcnt(2)
	v_and_b32_e32 v127, 0xffff0000, v102
	v_lshlrev_b32_e32 v124, 16, v102
	v_and_b32_e32 v125, 0xffff0000, v98
	v_pk_mul_f32 v[126:127], v[90:91], v[126:127] op_sel:[1,0] op_sel_hi:[0,1]
	v_pk_fma_f32 v[124:125], v[90:91], v[124:125], v[126:127]
	v_and_b32_e32 v127, 0xffff0000, v99
	v_lshlrev_b32_e32 v98, 16, v99
	v_and_b32_e32 v99, 0xffff0000, v103
	v_lshlrev_b32_e32 v126, 16, v103
	v_pk_mul_f32 v[98:99], v[90:91], v[98:99] op_sel:[1,0] op_sel_hi:[0,1]
	v_mul_f32_e32 v96, v96, v112
	s_waitcnt vmcnt(1)
	v_lshlrev_b32_e32 v102, 16, v107
	v_and_b32_e32 v103, 0xffff0000, v107
	v_pk_fma_f32 v[98:99], v[90:91], v[126:127], v[98:99]
	v_and_b32_e32 v111, 0xffff0000, v101
	v_lshlrev_b32_e32 v118, 16, v101
	v_pk_fma_f32 v[98:99], v[96:97], v[102:103], v[98:99] op_sel_hi:[0,1,1]
	v_and_b32_e32 v103, 0xffff0000, v100
	v_lshlrev_b32_e32 v100, 16, v100
	v_and_b32_e32 v101, 0xffff0000, v104
	v_and_b32_e32 v119, 0xffff0000, v105
	v_lshlrev_b32_e32 v102, 16, v104
	v_pk_mul_f32 v[100:101], v[90:91], v[100:101] op_sel:[1,0] op_sel_hi:[0,1]
	v_lshlrev_b32_e32 v110, 16, v105
	v_pk_fma_f32 v[100:101], v[90:91], v[102:103], v[100:101]
	v_pk_mul_f32 v[102:103], v[90:91], v[118:119] op_sel:[1,0] op_sel_hi:[0,1]
	v_lshlrev_b32_e32 v120, 16, v109
	v_and_b32_e32 v121, 0xffff0000, v109
	v_lshlrev_b32_e32 v128, 16, v106
	v_and_b32_e32 v129, 0xffff0000, v106
	s_waitcnt vmcnt(0)
; #define GAS __attribute__((address_space(1)))
; __device__ __forceinline__ unsigned pk2(float lo, float hi) { const f32x2_t v = {lo, hi}; const bf16x2_t b = __builtin_convertvector(v, bf16x2_t); return __builtin_bit_cast(unsigned, b); }
; __device__ __forceinline__ void merge_conv(const GAS bf16* proj, const GAS bf16* part, const GAS float* lse, GAS bf16* y, int TOKG, const GAS float* convw, int lane, int gw, int ngw) {
;     ...
;         for (int q = 0; q < 2; ++q) { const int it = it0 + q; const GAS bf16* pq = prow + (size_t)q * PW;
; #pragma unroll
;             for (int i = 0; i < 2; ++i) { const int c0 = lane * 8 + 512 * i, h = c0 >> 6;
;                 const float l0 = lse[((size_t)0 * TOKG + it) * 16 + h], l1 = lse[((size_t)1 * TOKG + it) * 16 + h], l2 = lse[((size_t)2 * TOKG + it) * 16 + h];
;                 const float mx = fmaxf(l0, fmaxf(l1, l2)); float w0 = __expf(l0 - mx), w1 = __expf(l1 - mx), w2 = __expf(l2 - mx); const float inv = __builtin_amdgcn_rcpf(w0 + w1 + w2); w0 *= inv; w1 *= inv; w2 *= inv;
;                 float a0[8], a1[8], a2[8], z[8];
;                 unpack8(*(const GAS v4u*)(part + ((size_t)0 * TOKG + it) * 1024 + c0), a0); unpack8(*(const GAS v4u*)(part + ((size_t)1 * TOKG + it) * 1024 + c0), a1); unpack8(*(const GAS v4u*)(part + ((size_t)2 * TOKG + it) * 1024 + c0), a2);
;                 unpack8(*(const GAS v4u*)(pq + 6144 + 1024 + c0), z);
;                 float r[8];
; #pragma unroll
;                 for (int e = 0; e < 8; ++e) r[e] = (w0 * a0[e] + w1 * a1[e] + w2 * a2[e]) * z[e];
;                 v4u o; o.x = pk2(r[0], r[1]); o.y = pk2(r[2], r[3]); o.z = pk2(r[4], r[5]); o.w = pk2(r[6], r[7]);
;                 *(GAS v4u*)(y + (size_t)it * MW + 1024 + c0) = o; } }
	v_lshlrev_b32_e32 v106, 16, v115
	v_and_b32_e32 v107, 0xffff0000, v115
	v_lshlrev_b32_e32 v104, 16, v108
	v_and_b32_e32 v105, 0xffff0000, v108
	v_pk_fma_f32 v[90:91], v[90:91], v[110:111], v[102:103]
	v_lshlrev_b32_e32 v122, 16, v117
	v_and_b32_e32 v123, 0xffff0000, v117
	v_lshlrev_b32_e32 v130, 16, v114
	v_and_b32_e32 v131, 0xffff0000, v114
	v_pk_fma_f32 v[124:125], v[96:97], v[128:129], v[124:125] op_sel_hi:[0,1,1]
	v_pk_mul_f32 v[98:99], v[98:99], v[106:107]
	v_lshlrev_b32_e32 v106, 16, v116
	v_and_b32_e32 v107, 0xffff0000, v116
	v_pk_fma_f32 v[100:101], v[96:97], v[104:105], v[100:101] op_sel_hi:[0,1,1]
	v_pk_fma_f32 v[90:91], v[96:97], v[120:121], v[90:91] op_sel_hi:[0,1,1]
	v_pk_mul_f32 v[124:125], v[124:125], v[130:131]
	v_pk_mul_f32 v[100:101], v[100:101], v[106:107]
	v_pk_mul_f32 v[90:91], v[90:91], v[122:123]
	v_cvt_pk_bf16_f32 v96, v124, v125
	v_cvt_pk_bf16_f32 v97, v98, v99
	v_cvt_pk_bf16_f32 v98, v100, v101
	v_cvt_pk_bf16_f32 v99, v90, v91
	global_store_dwordx4 v[60:61], v[96:99], off offset:3072 sc1
	global_load_dword v60, v[62:63], off offset:64
	s_nop 0
	global_load_dword v61, v[66:67], off offset:64
	s_nop 0
	global_load_dword v66, v[92:93], off offset:64
	s_nop 0
	global_load_dwordx4 v[90:93], v[58:59], off
	global_load_dwordx4 v[96:99], v[54:55], off
	global_load_dwordx4 v[100:103], v[64:65], off
	global_load_dwordx4 v[104:107], v[56:57], off offset:2048
	s_waitcnt vmcnt(3)
	v_lshlrev_b32_e32 v118, 16, v90
	s_waitcnt vmcnt(2)
	v_and_b32_e32 v119, 0xffff0000, v96
	v_max3_f32 v67, v60, v61, v66
	v_sub_f32_e32 v60, v60, v67
	v_mul_f32_e32 v60, 0x3fb8aa3b, v60
	v_exp_f32_e32 v63, v60
	v_sub_f32_e32 v60, v61, v67
	v_mul_f32_e32 v60, 0x3fb8aa3b, v60
	v_exp_f32_e32 v62, v60
	v_sub_f32_e32 v60, v66, v67
	v_mul_f32_e32 v60, 0x3fb8aa3b, v60
	v_exp_f32_e32 v60, v60
	v_add_f32_e32 v61, v63, v62
	v_lshlrev_b32_e32 v116, 16, v96
	v_and_b32_e32 v117, 0xffff0000, v90
	v_add_f32_e32 v61, v60, v61
	v_rcp_f32_e32 v66, v61
	v_lshlrev_b32_e32 v90, 16, v91
	s_waitcnt vmcnt(1)
	v_lshlrev_b32_e32 v96, 16, v101
	v_lshlrev_b32_e32 v108, 16, v93
	v_pk_mul_f32 v[62:63], v[62:63], v[66:67] op_sel_hi:[1,0]
	v_mul_f32_e32 v60, v60, v66
	v_pk_mul_f32 v[118:119], v[62:63], v[118:119] op_sel:[1,0] op_sel_hi:[0,1]
	v_pk_fma_f32 v[116:117], v[62:63], v[116:117], v[118:119]
	v_and_b32_e32 v119, 0xffff0000, v91
	v_and_b32_e32 v91, 0xffff0000, v97
	v_lshlrev_b32_e32 v118, 16, v97
	v_pk_mul_f32 v[90:91], v[62:63], v[90:91] op_sel:[1,0] op_sel_hi:[0,1]
	v_and_b32_e32 v97, 0xffff0000, v101
	v_pk_fma_f32 v[90:91], v[62:63], v[118:119], v[90:91]
	v_and_b32_e32 v67, 0xffff0000, v93
	v_pk_fma_f32 v[90:91], v[60:61], v[96:97], v[90:91] op_sel_hi:[0,1,1]
	v_and_b32_e32 v97, 0xffff0000, v92
	v_lshlrev_b32_e32 v92, 16, v92
	v_and_b32_e32 v93, 0xffff0000, v98
	v_and_b32_e32 v109, 0xffff0000, v99
	v_lshlrev_b32_e32 v96, 16, v98
	v_pk_mul_f32 v[92:93], v[62:63], v[92:93] op_sel:[1,0] op_sel_hi:[0,1]
	v_lshlrev_b32_e32 v66, 16, v99
	v_pk_fma_f32 v[92:93], v[62:63], v[96:97], v[92:93]
	v_pk_mul_f32 v[96:97], v[62:63], v[108:109] op_sel:[1,0] op_sel_hi:[0,1]
	v_lshlrev_b32_e32 v110, 16, v103
	v_and_b32_e32 v111, 0xffff0000, v103
	v_lshlrev_b32_e32 v120, 16, v100
	v_and_b32_e32 v121, 0xffff0000, v100
	s_waitcnt vmcnt(0)
; #define GAS __attribute__((address_space(1)))
; __device__ __forceinline__ unsigned pk2(float lo, float hi) { const f32x2_t v = {lo, hi}; const bf16x2_t b = __builtin_convertvector(v, bf16x2_t); return __builtin_bit_cast(unsigned, b); }
; __device__ __forceinline__ void merge_conv(const GAS bf16* proj, const GAS bf16* part, const GAS float* lse, GAS bf16* y, int TOKG, const GAS float* convw, int lane, int gw, int ngw) {
;     ...
;         for (int q = 0; q < 2; ++q) { const int it = it0 + q; const GAS bf16* pq = prow + (size_t)q * PW;
; #pragma unroll
;             for (int i = 0; i < 2; ++i) { const int c0 = lane * 8 + 512 * i, h = c0 >> 6;
;                 const float l0 = lse[((size_t)0 * TOKG + it) * 16 + h], l1 = lse[((size_t)1 * TOKG + it) * 16 + h], l2 = lse[((size_t)2 * TOKG + it) * 16 + h];
;                 const float mx = fmaxf(l0, fmaxf(l1, l2)); float w0 = __expf(l0 - mx), w1 = __expf(l1 - mx), w2 = __expf(l2 - mx); const float inv = __builtin_amdgcn_rcpf(w0 + w1 + w2); w0 *= inv; w1 *= inv; w2 *= inv;
;                 float a0[8], a1[8], a2[8], z[8];
;                 unpack8(*(const GAS v4u*)(part + ((size_t)0 * TOKG + it) * 1024 + c0), a0); unpack8(*(const GAS v4u*)(part + ((size_t)1 * TOKG + it) * 1024 + c0), a1); unpack8(*(const GAS v4u*)(part + ((size_t)2 * TOKG + it) * 1024 + c0), a2);
;                 unpack8(*(const GAS v4u*)(pq + 6144 + 1024 + c0), z);
;                 float r[8];
; #pragma unroll
;                 for (int e = 0; e < 8; ++e) r[e] = (w0 * a0[e] + w1 * a1[e] + w2 * a2[e]) * z[e];
;                 v4u o; o.x = pk2(r[0], r[1]); o.y = pk2(r[2], r[3]); o.z = pk2(r[4], r[5]); o.w = pk2(r[6], r[7]);
;                 *(GAS v4u*)(y + (size_t)it * MW + 1024 + c0) = o; } }
	v_lshlrev_b32_e32 v100, 16, v105
	v_and_b32_e32 v101, 0xffff0000, v105
	v_lshlrev_b32_e32 v98, 16, v102
	v_and_b32_e32 v99, 0xffff0000, v102
	v_pk_fma_f32 v[62:63], v[62:63], v[66:67], v[96:97]
	v_lshlrev_b32_e32 v114, 16, v107
	v_and_b32_e32 v115, 0xffff0000, v107
	v_lshlrev_b32_e32 v122, 16, v104
	v_and_b32_e32 v123, 0xffff0000, v104
	v_pk_fma_f32 v[116:117], v[60:61], v[120:121], v[116:117] op_sel_hi:[0,1,1]
	v_pk_mul_f32 v[90:91], v[90:91], v[100:101]
	v_lshlrev_b32_e32 v100, 16, v106
	v_and_b32_e32 v101, 0xffff0000, v106
	v_pk_fma_f32 v[92:93], v[60:61], v[98:99], v[92:93] op_sel_hi:[0,1,1]
	v_pk_fma_f32 v[60:61], v[60:61], v[110:111], v[62:63] op_sel_hi:[0,1,1]
	v_pk_mul_f32 v[116:117], v[116:117], v[122:123]
	v_pk_mul_f32 v[92:93], v[92:93], v[100:101]
	v_pk_mul_f32 v[66:67], v[60:61], v[114:115]
	v_cvt_pk_bf16_f32 v60, v116, v117
	v_cvt_pk_bf16_f32 v61, v90, v91
	v_cvt_pk_bf16_f32 v62, v92, v93
	v_cvt_pk_bf16_f32 v63, v66, v67
	global_store_dwordx4 v[52:53], v[60:63], off offset:2048 sc1
	global_load_dword v48, v[48:49], off offset:64
	s_nop 0
	global_load_dword v49, v[50:51], off offset:64
	s_nop 0
	global_load_dword v50, v[94:95], off offset:64
	s_waitcnt vmcnt(0)
	v_max3_f32 v51, v48, v49, v50
	v_sub_f32_e32 v48, v48, v51
	v_mul_f32_e32 v48, 0x3fb8aa3b, v48
	v_exp_f32_e32 v67, v48
	v_sub_f32_e32 v48, v49, v51
	v_mul_f32_e32 v48, 0x3fb8aa3b, v48
	v_exp_f32_e32 v66, v48
	v_sub_f32_e32 v48, v50, v51
	v_mul_f32_e32 v48, 0x3fb8aa3b, v48
	v_exp_f32_e32 v48, v48
	v_add_f32_e32 v49, v67, v66
	v_add_f32_e32 v49, v48, v49
	v_rcp_f32_e32 v90, v49
	s_nop 0
	v_mul_f32_e32 v92, v48, v90
	global_load_dwordx4 v[48:51], v[58:59], off offset:1024
	s_nop 0
	global_load_dwordx4 v[58:61], v[54:55], off offset:1024
	s_nop 0
	global_load_dwordx4 v[62:65], v[64:65], off offset:1024
	s_nop 0
	global_load_dwordx4 v[54:57], v[56:57], off offset:3072
	v_pk_mul_f32 v[66:67], v[66:67], v[90:91] op_sel_hi:[1,0]
	s_waitcnt vmcnt(3)
	v_lshlrev_b32_e32 v102, 16, v48
	s_waitcnt vmcnt(2)
	v_and_b32_e32 v103, 0xffff0000, v58
	v_lshlrev_b32_e32 v100, 16, v58
	v_and_b32_e32 v101, 0xffff0000, v48
	v_pk_mul_f32 v[102:103], v[66:67], v[102:103] op_sel:[1,0] op_sel_hi:[0,1]
	v_pk_fma_f32 v[100:101], v[66:67], v[100:101], v[102:103]
	v_and_b32_e32 v103, 0xffff0000, v49
	v_lshlrev_b32_e32 v48, 16, v49
	v_and_b32_e32 v49, 0xffff0000, v59
	v_lshlrev_b32_e32 v102, 16, v59
	v_pk_mul_f32 v[48:49], v[66:67], v[48:49] op_sel:[1,0] op_sel_hi:[0,1]
	s_waitcnt vmcnt(1)
	v_lshlrev_b32_e32 v58, 16, v63
	v_and_b32_e32 v59, 0xffff0000, v63
	v_pk_fma_f32 v[48:49], v[66:67], v[102:103], v[48:49]
	s_waitcnt vmcnt(0)
	v_lshlrev_b32_e32 v106, 16, v54
	v_and_b32_e32 v107, 0xffff0000, v54
	v_lshlrev_b32_e32 v54, 16, v55
	v_and_b32_e32 v55, 0xffff0000, v55
	v_pk_fma_f32 v[48:49], v[92:93], v[58:59], v[48:49] op_sel_hi:[0,1,1]
	v_and_b32_e32 v91, 0xffff0000, v51
	v_lshlrev_b32_e32 v94, 16, v51
	v_pk_mul_f32 v[54:55], v[48:49], v[54:55]
	v_and_b32_e32 v49, 0xffff0000, v50
	v_lshlrev_b32_e32 v50, 16, v50
	v_and_b32_e32 v51, 0xffff0000, v60
	v_lshlrev_b32_e32 v48, 16, v60
	v_pk_mul_f32 v[50:51], v[66:67], v[50:51] op_sel:[1,0] op_sel_hi:[0,1]
	v_lshlrev_b32_e32 v58, 16, v64
	v_and_b32_e32 v59, 0xffff0000, v64
	v_pk_fma_f32 v[48:49], v[66:67], v[48:49], v[50:51]
	v_lshlrev_b32_e32 v90, 16, v61
	v_and_b32_e32 v95, 0xffff0000, v61
	v_lshlrev_b32_e32 v60, 16, v56
	v_and_b32_e32 v61, 0xffff0000, v56
	v_pk_fma_f32 v[48:49], v[92:93], v[58:59], v[48:49] op_sel_hi:[0,1,1]
	v_pk_mul_f32 v[50:51], v[48:49], v[60:61]
	v_pk_mul_f32 v[48:49], v[66:67], v[94:95] op_sel:[1,0] op_sel_hi:[0,1]
	v_lshlrev_b32_e32 v96, 16, v65
	v_and_b32_e32 v97, 0xffff0000, v65
	v_lshlrev_b32_e32 v104, 16, v62
	v_and_b32_e32 v105, 0xffff0000, v62
	v_pk_fma_f32 v[48:49], v[66:67], v[90:91], v[48:49]
	v_lshlrev_b32_e32 v98, 16, v57
	v_and_b32_e32 v99, 0xffff0000, v57
	v_pk_fma_f32 v[100:101], v[92:93], v[104:105], v[100:101] op_sel_hi:[0,1,1]
	v_pk_fma_f32 v[48:49], v[92:93], v[96:97], v[48:49] op_sel_hi:[0,1,1]
	v_pk_mul_f32 v[100:101], v[100:101], v[106:107]
	v_pk_mul_f32 v[56:57], v[48:49], v[98:99]
	v_cvt_pk_bf16_f32 v48, v100, v101
	v_cvt_pk_bf16_f32 v49, v54, v55
	v_cvt_pk_bf16_f32 v50, v50, v51
	v_cvt_pk_bf16_f32 v51, v56, v57
	global_store_dwordx4 v[52:53], v[48:51], off offset:3072 sc1
	s_cbranch_scc1 .LBB0_413

; #define GAS __attribute__((address_space(1)))
; __device__ __forceinline__ unsigned pk2(float lo, float hi) { const f32x2_t v = {lo, hi}; const bf16x2_t b = __builtin_convertvector(v, bf16x2_t); return __builtin_bit_cast(unsigned, b); }
; __device__ __forceinline__ void merge_conv(const GAS bf16* proj, const GAS bf16* part, const GAS float* lse, GAS bf16* y, int TOKG, const GAS float* convw, int lane, int gw, int ngw) {
;     ...
;         for (int i = 0; i < 2; ++i) { const int c0 = lane * 8 + 512 * i;
;             float u[4][8];
; #pragma unroll
;             for (int k = 0; k < 4; ++k) { const int tt = t - 2 + k;
;                 if (tt >= 0) { const GAS bf16* pr = prow + ((ptrdiff_t)k - 2) * PW; float gc[8], xa[8];
;                     unpack8(*(const GAS v4u*)(pr + 1024 + c0), gc); unpack8(*(const GAS v4u*)(pr + 2048 + c0), xa);
; #pragma unroll
;                     for (int e = 0; e < 8; ++e) u[k][e] = gc[e] * xa[e]; }
;                 else {
; #pragma unroll
;                     for (int e = 0; e < 8; ++e) u[k][e] = 0.f; } }
; #pragma unroll
;             for (int q = 0; q < 2; ++q) { const GAS bf16* pq = prow + (size_t)q * PW;
;                 float gb[8], z[8], r[8]; unpack8(*(const GAS v4u*)(pq + c0), gb); unpack8(*(const GAS v4u*)(pq + 6144 + c0), z);
; #pragma unroll
;                 for (int e = 0; e < 8; ++e) r[e] = gb[e] * (cw[i][0][e] * u[q][e] + cw[i][1][e] * u[q + 1][e] + cw[i][2][e] * u[q + 2][e]) * z[e];
;                 v4u o; o.x = pk2(r[0], r[1]); o.y = pk2(r[2], r[3]); o.z = pk2(r[4], r[5]); o.w = pk2(r[6], r[7]);
;                 *(GAS v4u*)(y + (size_t)(it0 + q) * MW + c0) = o; } }
.LBB0_409:
	v_add_co_u32_e32 v96, vcc, s86, v94
	s_mov_b32 s3, 0x1804000
	s_nop 0
	v_addc_co_u32_e32 v97, vcc, 0, v95, vcc
	v_add_co_u32_e32 v98, vcc, s68, v94
	global_load_dwordx4 v[56:59], v[96:97], off offset:2048
	s_nop 0
	v_addc_co_u32_e32 v99, vcc, 0, v95, vcc
	v_add_co_u32_e32 v92, vcc, s3, v94
	s_mov_b32 s3, 0x1805000
	s_nop 0
	v_addc_co_u32_e32 v93, vcc, 0, v95, vcc
	global_load_dwordx4 v[60:63], v[98:99], off
	v_add_co_u32_e32 v100, vcc, s3, v94
	global_load_dwordx4 v[48:51], v[92:93], off offset:2048
	s_nop 0
	v_addc_co_u32_e32 v101, vcc, 0, v95, vcc
	global_load_dwordx4 v[52:55], v[100:101], off
	global_load_dwordx4 v[64:67], v[96:97], off
	global_load_dwordx4 v[122:125], v[92:93], off offset:-4096
	v_pk_mul_f32 v[130:131], v[28:29], v[108:109]
	s_mov_b32 s3, 0x1803000
	v_pk_fma_f32 v[120:121], v[40:41], v[120:121], v[130:131]
	v_add_co_u32_e32 v90, vcc, s3, v94
	s_mov_b32 s3, 0x1807000
	s_nop 0
	v_addc_co_u32_e32 v91, vcc, 0, v95, vcc
	s_waitcnt vmcnt(5)
	v_lshlrev_b32_e32 v116, 16, v56
	v_and_b32_e32 v117, 0xffff0000, v56
	v_lshlrev_b32_e32 v56, 16, v57
	v_and_b32_e32 v57, 0xffff0000, v57
	s_waitcnt vmcnt(4)
	v_lshlrev_b32_e32 v126, 16, v60
	v_and_b32_e32 v127, 0xffff0000, v60
	v_pk_mul_f32 v[116:117], v[116:117], v[126:127]
	v_lshlrev_b32_e32 v60, 16, v61
	v_pk_fma_f32 v[120:121], v[20:21], v[116:117], v[120:121]
	v_and_b32_e32 v61, 0xffff0000, v61
	s_waitcnt vmcnt(1)
	v_lshlrev_b32_e32 v126, 16, v64
	v_and_b32_e32 v127, 0xffff0000, v64
	s_waitcnt vmcnt(0)
	v_lshlrev_b32_e32 v128, 16, v122
	v_and_b32_e32 v129, 0xffff0000, v122
	v_pk_mul_f32 v[120:121], v[120:121], v[126:127]
	v_pk_mul_f32 v[116:117], v[28:29], v[116:117]
	v_pk_mul_f32 v[126:127], v[120:121], v[128:129]
	v_pk_mul_f32 v[120:121], v[56:57], v[60:61]
	v_lshlrev_b32_e32 v56, 16, v65
	v_and_b32_e32 v57, 0xffff0000, v65
	v_pk_mul_f32 v[64:65], v[30:31], v[106:107]
	v_lshlrev_b32_e32 v60, 16, v123
	v_pk_fma_f32 v[64:65], v[42:43], v[118:119], v[64:65]
	v_and_b32_e32 v61, 0xffff0000, v123
	v_pk_fma_f32 v[64:65], v[22:23], v[120:121], v[64:65]
	v_pk_mul_f32 v[122:123], v[36:37], v[104:105]
	v_pk_mul_f32 v[56:57], v[64:65], v[56:57]
	v_lshlrev_b32_e32 v64, 16, v62
	v_pk_mul_f32 v[60:61], v[56:57], v[60:61]
	v_lshlrev_b32_e32 v56, 16, v58
	v_and_b32_e32 v57, 0xffff0000, v58
	v_and_b32_e32 v65, 0xffff0000, v62
	v_pk_mul_f32 v[64:65], v[56:57], v[64:65]
	v_pk_fma_f32 v[114:115], v[44:45], v[114:115], v[122:123]
	v_lshlrev_b32_e32 v56, 16, v66
	v_and_b32_e32 v57, 0xffff0000, v66
	v_pk_fma_f32 v[114:115], v[32:33], v[64:65], v[114:115]
	v_lshlrev_b32_e32 v118, 16, v124
	v_and_b32_e32 v119, 0xffff0000, v124
	v_pk_mul_f32 v[56:57], v[114:115], v[56:57]
	v_lshlrev_b32_e32 v58, 16, v63
	v_pk_mul_f32 v[118:119], v[56:57], v[118:119]
	v_lshlrev_b32_e32 v56, 16, v59
	v_and_b32_e32 v57, 0xffff0000, v59
	v_and_b32_e32 v59, 0xffff0000, v63
	v_pk_mul_f32 v[62:63], v[38:39], v[102:103]
	v_pk_mul_f32 v[114:115], v[56:57], v[58:59]
	v_pk_fma_f32 v[62:63], v[46:47], v[110:111], v[62:63]
	v_lshlrev_b32_e32 v56, 16, v67
	v_and_b32_e32 v57, 0xffff0000, v67
	v_pk_fma_f32 v[62:63], v[34:35], v[114:115], v[62:63]
	v_lshlrev_b32_e32 v58, 16, v125
	v_and_b32_e32 v59, 0xffff0000, v125
	v_pk_mul_f32 v[56:57], v[62:63], v[56:57]
	v_lshlrev_b32_e32 v66, 16, v48
	v_pk_mul_f32 v[62:63], v[56:57], v[58:59]
	v_cvt_pk_bf16_f32 v57, v60, v61
	v_cvt_pk_bf16_f32 v59, v62, v63
	v_lshl_add_u64 v[62:63], s[0:1], 0, v[88:89]
	v_add_co_u32_e32 v60, vcc, s86, v62
	v_cvt_pk_bf16_f32 v56, v126, v127
	v_cvt_pk_bf16_f32 v58, v118, v119
	v_addc_co_u32_e32 v61, vcc, 0, v63, vcc
	global_store_dwordx4 v[60:61], v[56:59], off sc1
	global_load_dwordx4 v[122:125], v[92:93], off
	v_and_b32_e32 v67, 0xffff0000, v48
	v_add_co_u32_e32 v56, vcc, s3, v94
	v_lshlrev_b32_e32 v58, 16, v52
	s_nop 0
	v_addc_co_u32_e32 v57, vcc, 0, v95, vcc
	global_load_dwordx4 v[126:129], v[56:57], off
	v_and_b32_e32 v59, 0xffff0000, v52
	v_pk_mul_f32 v[58:59], v[66:67], v[58:59]
	v_pk_fma_f32 v[108:109], v[40:41], v[108:109], v[116:117]
	v_lshlrev_b32_e32 v52, 16, v53
	v_pk_fma_f32 v[58:59], v[20:21], v[58:59], v[108:109]
	v_and_b32_e32 v53, 0xffff0000, v53
	v_lshlrev_b32_e32 v48, 16, v49
	v_and_b32_e32 v49, 0xffff0000, v49
	v_pk_mul_f32 v[108:109], v[30:31], v[120:121]
	v_pk_mul_f32 v[48:49], v[48:49], v[52:53]
	v_pk_fma_f32 v[106:107], v[42:43], v[106:107], v[108:109]
	v_pk_mul_f32 v[64:65], v[36:37], v[64:65]
	v_pk_fma_f32 v[48:49], v[22:23], v[48:49], v[106:107]
	v_pk_fma_f32 v[64:65], v[44:45], v[104:105], v[64:65]
	v_mov_b32_e32 v108, 0
	v_mov_b32_e32 v109, 0
	s_waitcnt vmcnt(1)
	v_lshlrev_b32_e32 v66, 16, v122
	v_and_b32_e32 v67, 0xffff0000, v122
	v_lshlrev_b32_e32 v52, 16, v123
	v_and_b32_e32 v53, 0xffff0000, v123
	v_pk_mul_f32 v[58:59], v[58:59], v[66:67]
	v_pk_mul_f32 v[48:49], v[48:49], v[52:53]
	s_waitcnt vmcnt(0)
	v_lshlrev_b32_e32 v66, 16, v127
	v_and_b32_e32 v67, 0xffff0000, v127
	v_pk_mul_f32 v[52:53], v[48:49], v[66:67]
	v_lshlrev_b32_e32 v48, 16, v54
	v_and_b32_e32 v49, 0xffff0000, v54
	v_lshlrev_b32_e32 v66, 16, v50
	v_and_b32_e32 v67, 0xffff0000, v50
	v_pk_mul_f32 v[48:49], v[66:67], v[48:49]
	v_lshlrev_b32_e32 v66, 16, v124
	v_and_b32_e32 v67, 0xffff0000, v124
	v_pk_fma_f32 v[48:49], v[32:33], v[48:49], v[64:65]
	v_lshlrev_b32_e32 v106, 16, v128
	v_and_b32_e32 v107, 0xffff0000, v128
	v_pk_mul_f32 v[48:49], v[48:49], v[66:67]
	v_lshlrev_b32_e32 v50, 16, v51
	v_pk_mul_f32 v[64:65], v[48:49], v[106:107]
	v_lshlrev_b32_e32 v48, 16, v55
	v_and_b32_e32 v49, 0xffff0000, v55
	v_and_b32_e32 v51, 0xffff0000, v51
	v_pk_mul_f32 v[66:67], v[38:39], v[114:115]
	v_pk_mul_f32 v[48:49], v[50:51], v[48:49]
	v_pk_fma_f32 v[66:67], v[46:47], v[102:103], v[66:67]
	v_lshlrev_b32_e32 v50, 16, v125
	v_and_b32_e32 v51, 0xffff0000, v125
	v_pk_fma_f32 v[48:49], v[34:35], v[48:49], v[66:67]
	v_lshlrev_b32_e32 v54, 16, v129
	v_and_b32_e32 v55, 0xffff0000, v129
	v_pk_mul_f32 v[48:49], v[48:49], v[50:51]
	v_lshlrev_b32_e32 v110, 16, v126
	v_and_b32_e32 v111, 0xffff0000, v126
	v_pk_mul_f32 v[54:55], v[48:49], v[54:55]
	v_cvt_pk_bf16_f32 v49, v52, v53
	v_add_co_u32_e32 v52, vcc, 0x1801000, v62
	v_pk_mul_f32 v[58:59], v[58:59], v[110:111]
	s_nop 0
	v_addc_co_u32_e32 v53, vcc, 0, v63, vcc
	v_cvt_pk_bf16_f32 v48, v58, v59
	v_cvt_pk_bf16_f32 v50, v64, v65
	v_cvt_pk_bf16_f32 v51, v54, v55
	v_mov_b32_e32 v58, 0
	s_and_b64 vcc, exec, s[4:5]
	v_mov_b32_e32 v64, 0
	v_mov_b32_e32 v65, 0
	v_mov_b32_e32 v66, 0
	v_mov_b32_e32 v67, 0
	v_mov_b32_e32 v110, 0
	v_mov_b32_e32 v111, 0
	global_store_dwordx4 v[52:53], v[48:51], off sc1
	s_cbranch_vccnz .LBB0_411
; #define GAS __attribute__((address_space(1)))
; __device__ __forceinline__ void merge_conv(const GAS bf16* proj, const GAS bf16* part, const GAS float* lse, GAS bf16* y, int TOKG, const GAS float* convw, int lane, int gw, int ngw) {
;     ...
;             for (int k = 0; k < 4; ++k) { const int tt = t - 2 + k;
;                 if (tt >= 0) { const GAS bf16* pr = prow + ((ptrdiff_t)k - 2) * PW; float gc[8], xa[8];
;                     unpack8(*(const GAS v4u*)(pr + 1024 + c0), gc); unpack8(*(const GAS v4u*)(pr + 2048 + c0), xa);
; #pragma unroll
;                     for (int e = 0; e < 8; ++e) u[k][e] = gc[e] * xa[e]; }
	s_nop 0
	v_add_co_u32_e32 v48, vcc, 0x17f8000, v94
	s_nop 1
	v_addc_co_u32_e32 v49, vcc, 0, v95, vcc
	v_add_co_u32_e32 v52, vcc, 0x17f9000, v94
	global_load_dwordx4 v[48:51], v[48:49], off offset:3072
	s_nop 0
	v_addc_co_u32_e32 v53, vcc, 0, v95, vcc
	global_load_dwordx4 v[52:55], v[52:53], off offset:1024
	s_waitcnt vmcnt(1)
	v_lshlrev_b32_e32 v64, 16, v48
	v_and_b32_e32 v65, 0xffff0000, v48
	v_lshlrev_b32_e32 v48, 16, v49
	s_waitcnt vmcnt(0)
	v_lshlrev_b32_e32 v66, 16, v52
	v_and_b32_e32 v67, 0xffff0000, v52
	v_and_b32_e32 v49, 0xffff0000, v49
	v_lshlrev_b32_e32 v52, 16, v53
	v_and_b32_e32 v53, 0xffff0000, v53
	v_pk_mul_f32 v[108:109], v[48:49], v[52:53]
	v_lshlrev_b32_e32 v48, 16, v50
	v_and_b32_e32 v49, 0xffff0000, v50
	v_lshlrev_b32_e32 v52, 16, v54
	v_and_b32_e32 v53, 0xffff0000, v54
	v_pk_mul_f32 v[110:111], v[64:65], v[66:67]
	v_pk_mul_f32 v[66:67], v[48:49], v[52:53]
	v_lshlrev_b32_e32 v48, 16, v51
	v_and_b32_e32 v49, 0xffff0000, v51
	v_lshlrev_b32_e32 v50, 16, v55
	v_and_b32_e32 v51, 0xffff0000, v55
	v_pk_mul_f32 v[64:65], v[48:49], v[50:51]
